# P6 row loop: sum-of-squares wait moved below the 16 row loads (loads no longer wait for the previous iteration's stores)
# speedup vs baseline: 1.0328x; 1.0019x over previous
; __device__ __forceinline__ float bf2f(unsigned v) { return __uint_as_float(v << 16); }
; __device__ __forceinline__ unsigned pk2(float lo, float hi) { f32x2 v; v.x = lo; v.y = hi; return __builtin_bit_cast(unsigned, __builtin_convertvector(v, hwbf2)); }
; __global__ void __launch_bounds__(512, 2) fwd_kernel(Args a) {
;     ...
;         for (int row0 = 2 * gw; row0 < R; row0 += 2 * NGW) {
;             f32x4 xv[2][4]; u32x2 mm[2][4]; float rs[2];
; #pragma unroll
;             for (int rr = 0; rr < 2; ++rr) { const int row = row0 + rr;
;                 rs[rr] = s2[row];
; #pragma unroll
;                 for (int q = 0; q < 4; ++q) { const u32x2 xx = *(const u32x2*)(hb + (size_t)row * DM + q * 256 + lane * 4);
;                     xv[rr][q][0] = bf2f(xx.x & 0xffff); xv[rr][q][1] = bf2f(xx.x >> 16); xv[rr][q][2] = bf2f(xx.y & 0xffff); xv[rr][q][3] = bf2f(xx.y >> 16);
;                     mm[rr][q] = *(const u32x2*)(mix + (size_t)row * DM + q * 256 + lane * 4); } }
; #pragma unroll
;             for (int rr = 0; rr < 2; ++rr) { const int row = row0 + rr;
;                 const float r_ = 1.f / sqrtf(rs[rr] * (1.f / DM) + EPS);
;                 float ss = 0.f; f32x4 hv[4];
; #pragma unroll
;                 for (int q = 0; q < 4; ++q) { const u32x2 m2 = mm[rr][q];
;                     hv[q][0] = xv[rr][q][0] + bf2f(m2.x & 0xffff) * r_ * w4[q][0]; hv[q][1] = xv[rr][q][1] + bf2f(m2.x >> 16) * r_ * w4[q][1]; hv[q][2] = xv[rr][q][2] + bf2f(m2.y & 0xffff) * r_ * w4[q][2]; hv[q][3] = xv[rr][q][3] + bf2f(m2.y >> 16) * r_ * w4[q][3];
;                     ss += (hv[q][0] * hv[q][0] + hv[q][1] * hv[q][1]) + (hv[q][2] * hv[q][2] + hv[q][3] * hv[q][3]); }
;                 ss = wave_sum(ss);
; #pragma unroll
;                 for (int q = 0; q < 4; ++q) { u32x2 w; w.x = pk2(hv[q][0], hv[q][1]); w.y = pk2(hv[q][2], hv[q][3]); *(u32x2*)(hb + (size_t)row * DM + q * 256 + lane * 4) = w; }
;                 if (lane == 0) rstd3[row] = 1.f / sqrtf(ss * (1.f / DM) + EPS); }
.LBB0_1053:
	s_add_u32 s34, s88, s10
	s_addc_u32 s35, s89, s11
	global_load_dwordx2 v[26:27], v40, s[34:35]
	v_lshl_add_u64 v[32:33], s[88:89], 0, v[16:17]
	v_add_co_u32_e32 v38, vcc, 0x2400000, v32
	v_addc_co_u32_e32 v39, vcc, 0, v33, vcc
	v_add_co_u32_e32 v54, vcc, 0x2ae00000, v32
	global_load_dwordx2 v[46:47], v[38:39], off
	global_load_dwordx2 v[48:49], v[38:39], off offset:512
	global_load_dwordx2 v[50:51], v[38:39], off offset:1024
	global_load_dwordx2 v[52:53], v[38:39], off offset:1536
	v_addc_co_u32_e32 v55, vcc, 0, v33, vcc
	global_load_dwordx2 v[56:57], v[54:55], off
	global_load_dwordx2 v[58:59], v[54:55], off offset:512
	global_load_dwordx2 v[60:61], v[54:55], off offset:1024
	global_load_dwordx2 v[62:63], v[54:55], off offset:1536
	global_load_dwordx2 v[36:37], v[38:39], off offset:2048
	global_load_dwordx2 v[34:35], v[38:39], off offset:2560
	global_load_dwordx2 v[30:31], v[38:39], off offset:3072
	global_load_dwordx2 v[24:25], v[54:55], off offset:2048
	global_load_dwordx2 v[22:23], v[54:55], off offset:2560
	global_load_dwordx2 v[20:21], v[54:55], off offset:3072
	global_load_dwordx2 v[28:29], v[38:39], off offset:3584
	global_load_dwordx2 v[18:19], v[54:55], off offset:3584
	s_waitcnt vmcnt(16)
	v_fmamk_f32 v26, v26, 0x3a800000, v41
	v_mul_f32_e32 v45, 0x4f800000, v26
	v_cmp_gt_f32_e32 vcc, s7, v26
	s_waitcnt vmcnt(11)
	v_lshlrev_b32_e32 v70, 16, v56
	v_cndmask_b32_e32 v26, v26, v45, vcc
	v_sqrt_f32_e32 v45, v26
	s_waitcnt vmcnt(8)
	v_lshlrev_b32_e32 v76, 16, v62
	v_and_b32_e32 v77, 0xffff0000, v62
	v_and_b32_e32 v71, 0xffff0000, v56
	v_add_u32_e32 v62, -1, v45
	v_add_u32_e32 v78, 1, v45
	v_fma_f32 v79, -v62, v45, v26
	v_fma_f32 v80, -v78, v45, v26
	v_cmp_ge_f32_e64 s[2:3], 0, v79
	v_lshlrev_b32_e32 v56, 16, v57
	v_and_b32_e32 v57, 0xffff0000, v57
	v_cndmask_b32_e64 v45, v45, v62, s[2:3]
	v_cmp_lt_f32_e64 s[2:3], 0, v80
	v_lshlrev_b32_e32 v72, 16, v58
	v_and_b32_e32 v73, 0xffff0000, v58
	v_cndmask_b32_e64 v45, v45, v78, s[2:3]
	v_mul_f32_e32 v62, 0x37800000, v45
	v_cndmask_b32_e32 v45, v45, v62, vcc
	v_cmp_class_f32_e32 vcc, v26, v42
	v_lshlrev_b32_e32 v58, 16, v59
	v_and_b32_e32 v59, 0xffff0000, v59
	v_cndmask_b32_e32 v26, v45, v26, vcc
	v_div_scale_f32 v45, s[2:3], v26, v26, 1.0
	v_rcp_f32_e32 v78, v45
	v_div_scale_f32 v79, vcc, 1.0, v26, 1.0
	v_lshlrev_b32_e32 v54, 16, v46
	v_fma_f32 v80, -v45, v78, 1.0
	v_fmac_f32_e32 v78, v80, v78
	v_mul_f32_e32 v80, v79, v78
	v_fma_f32 v81, -v45, v80, v79
	v_fmac_f32_e32 v80, v81, v78
	v_fma_f32 v45, -v45, v80, v79
	v_div_fmas_f32 v45, v45, v78, v80
	v_div_fixup_f32 v26, v45, v26, 1.0
	v_and_b32_e32 v55, 0xffff0000, v46
	v_lshlrev_b32_e32 v46, 16, v47
	v_and_b32_e32 v47, 0xffff0000, v47
	v_lshlrev_b32_e32 v64, 16, v48
	v_and_b32_e32 v65, 0xffff0000, v48
	v_lshlrev_b32_e32 v48, 16, v49
	v_and_b32_e32 v49, 0xffff0000, v49
	v_lshlrev_b32_e32 v74, 16, v60
	v_and_b32_e32 v75, 0xffff0000, v60
	v_lshlrev_b32_e32 v60, 16, v61
	v_and_b32_e32 v61, 0xffff0000, v61
	v_pk_mul_f32 v[56:57], v[26:27], v[56:57] op_sel_hi:[0,1]
	v_pk_mul_f32 v[72:73], v[26:27], v[72:73] op_sel_hi:[0,1]
	v_pk_mul_f32 v[58:59], v[26:27], v[58:59] op_sel_hi:[0,1]
	v_lshlrev_b32_e32 v66, 16, v50
	v_and_b32_e32 v67, 0xffff0000, v50
	v_lshlrev_b32_e32 v50, 16, v51
	v_and_b32_e32 v51, 0xffff0000, v51
	v_lshlrev_b32_e32 v68, 16, v52
	v_and_b32_e32 v69, 0xffff0000, v52
	v_pk_mul_f32 v[70:71], v[26:27], v[70:71] op_sel_hi:[0,1]
	v_pk_mul_f32 v[60:61], v[26:27], v[60:61] op_sel_hi:[0,1]
	v_pk_mul_f32 v[76:77], v[26:27], v[76:77] op_sel_hi:[0,1]
	v_pk_fma_f32 v[46:47], v[14:15], v[56:57], v[46:47]
	v_pk_fma_f32 v[56:57], v[8:9], v[72:73], v[64:65]
	v_pk_fma_f32 v[48:49], v[10:11], v[58:59], v[48:49]
	v_lshlrev_b32_e32 v62, 16, v63
	v_pk_mul_f32 v[74:75], v[26:27], v[74:75] op_sel_hi:[0,1]
	v_pk_fma_f32 v[54:55], v[12:13], v[70:71], v[54:55]
	v_pk_fma_f32 v[50:51], v[6:7], v[60:61], v[50:51]
	v_pk_fma_f32 v[60:61], v[0:1], v[76:77], v[68:69]
	v_pk_mul_f32 v[68:69], v[56:57], v[56:57]
	v_pk_mul_f32 v[70:71], v[48:49], v[48:49]
	v_and_b32_e32 v63, 0xffff0000, v63
	v_pk_fma_f32 v[58:59], v[4:5], v[74:75], v[66:67]
	v_pk_mul_f32 v[64:65], v[54:55], v[54:55]
	v_pk_mul_f32 v[66:67], v[46:47], v[46:47]
	v_pk_mul_f32 v[62:63], v[26:27], v[62:63] op_sel_hi:[0,1]
	v_add_f32_e32 v26, v70, v71
	v_add_f32_e32 v45, v68, v69
	v_add_f32_e32 v26, v45, v26
	v_add_f32_e32 v45, v66, v67
	v_add_f32_e32 v64, v64, v65
	v_lshlrev_b32_e32 v52, 16, v53
	v_and_b32_e32 v53, 0xffff0000, v53
	v_pk_mul_f32 v[72:73], v[58:59], v[58:59]
	v_pk_mul_f32 v[74:75], v[50:51], v[50:51]
	v_add_f32_e32 v45, v64, v45
	v_pk_fma_f32 v[52:53], v[2:3], v[62:63], v[52:53]
	v_add_f32_e32 v26, v45, v26
	v_add_f32_e32 v45, v74, v75
	v_add_f32_e32 v64, v72, v73
	v_pk_mul_f32 v[62:63], v[60:61], v[60:61]
	v_pk_mul_f32 v[76:77], v[52:53], v[52:53]
	v_add_f32_e32 v45, v64, v45
	v_add_f32_e32 v26, v26, v45
	v_add_f32_e32 v45, v76, v77
	v_add_f32_e32 v62, v62, v63
	v_add_f32_e32 v45, v62, v45
	v_add_f32_e32 v26, v26, v45
	v_mov_b32_e32 v45, 0
	v_cvt_pk_bf16_f32 v54, v54, v55
	v_add_f32_dpp v26, v26, v26 quad_perm:[1,0,3,2] row_mask:0xf bank_mask:0xf bound_ctrl:1
	v_cvt_pk_bf16_f32 v55, v46, v47
	v_cvt_pk_bf16_f32 v46, v56, v57
	v_add_f32_dpp v26, v26, v26 quad_perm:[2,3,0,1] row_mask:0xf bank_mask:0xf bound_ctrl:1
	v_cvt_pk_bf16_f32 v47, v48, v49
	global_store_dwordx2 v[38:39], v[46:47], off offset:512
	v_add_f32_dpp v26, v26, v26 row_half_mirror row_mask:0xf bank_mask:0xf bound_ctrl:1
	v_cvt_pk_bf16_f32 v46, v58, v59
	v_cvt_pk_bf16_f32 v47, v50, v51
	v_add_f32_dpp v26, v26, v26 row_mirror row_mask:0xf bank_mask:0xf bound_ctrl:1
	global_store_dwordx2 v[38:39], v[46:47], off offset:1024
	v_cvt_pk_bf16_f32 v46, v60, v61
	v_mov_b32_dpp v45, v26 row_bcast:15 row_mask:0xa bank_mask:0xf
	v_add_f32_e32 v26, v26, v45
	v_mov_b32_e32 v45, 0
	v_cvt_pk_bf16_f32 v47, v52, v53
	global_store_dwordx2 v[38:39], v[54:55], off
	v_mov_b32_dpp v45, v26 row_bcast:31 row_mask:0xc bank_mask:0xf
	v_add_f32_e32 v26, v26, v45
	global_store_dwordx2 v[38:39], v[46:47], off offset:1536
	v_readlane_b32 s2, v26, 63
	s_and_saveexec_b64 s[36:37], s[0:1]
	s_cbranch_execz .LBB0_1055
; __device__ __forceinline__ unsigned pk2(float lo, float hi) { f32x2 v; v.x = lo; v.y = hi; return __builtin_bit_cast(unsigned, __builtin_convertvector(v, hwbf2)); }
; __global__ void __launch_bounds__(512, 2) fwd_kernel(Args a) {
;     ...
;                 ss = wave_sum(ss);
; #pragma unroll
;                 for (int q = 0; q < 4; ++q) { u32x2 w; w.x = pk2(hv[q][0], hv[q][1]); w.y = pk2(hv[q][2], hv[q][3]); *(u32x2*)(hb + (size_t)row * DM + q * 256 + lane * 4) = w; }
;                 if (lane == 0) rstd3[row] = 1.f / sqrtf(ss * (1.f / DM) + EPS); }
	v_fma_f32 v26, s2, v44, v41
	v_mul_f32_e32 v38, 0x4f800000, v26
	v_cmp_gt_f32_e32 vcc, s7, v26
	s_nop 1
	v_cndmask_b32_e32 v26, v26, v38, vcc
	v_sqrt_f32_e32 v38, v26
	s_nop 0
	v_add_u32_e32 v39, -1, v38
	v_fma_f32 v46, -v39, v38, v26
	v_add_u32_e32 v45, 1, v38
	v_cmp_ge_f32_e64 s[2:3], 0, v46
	s_nop 1
	v_cndmask_b32_e64 v39, v38, v39, s[2:3]
	v_fma_f32 v38, -v45, v38, v26
	v_cmp_lt_f32_e64 s[2:3], 0, v38
	s_nop 1
	v_cndmask_b32_e64 v38, v39, v45, s[2:3]
	v_mul_f32_e32 v39, 0x37800000, v38
	v_cndmask_b32_e32 v38, v38, v39, vcc
	v_cmp_class_f32_e32 vcc, v26, v42
	s_nop 1
	v_cndmask_b32_e32 v26, v38, v26, vcc
	v_div_scale_f32 v38, s[2:3], v26, v26, 1.0
	v_rcp_f32_e32 v39, v38
	s_nop 0
	v_fma_f32 v45, -v38, v39, 1.0
	v_fmac_f32_e32 v39, v45, v39
	v_div_scale_f32 v45, vcc, 1.0, v26, 1.0
	v_mul_f32_e32 v46, v45, v39
	v_fma_f32 v47, -v38, v46, v45
	v_fmac_f32_e32 v46, v47, v39
	v_fma_f32 v38, -v38, v46, v45
	v_div_fmas_f32 v38, v38, v39, v46
	v_div_fixup_f32 v26, v38, v26, 1.0
	global_store_dword v43, v26, s[34:35]
